# v38 + strategy 7: LayerNorm-1 wave_sum xor-1/xor-2 steps via v_add_f32_dpp quad_perm instead of ds_bpermute round trips
# baseline (speedup 1.0000x reference)
; __device__ __forceinline__ float wave_sum(float v) {
; #pragma unroll
;     for (int o = 1; o < 64; o <<= 1) v += __shfl_xor(v, o);
;     return v;
; __device__ __forceinline__ void ln_apply(f32x4 (&v)[8], const float* __restrict__ g, const float* __restrict__ b, bf16_t* hb, float* fo, int lane) {
;     float s = 0.f;
; #pragma unroll
;     for (int j = 0; j < 8; ++j) s += (v[j][0] + v[j][1]) + (v[j][2] + v[j][3]);
;     const float mean = wave_sum(s) * (1.f / DM); float q = 0.f;
; #pragma unroll
;     for (int j = 0; j < 8; ++j) { v[j] = v[j] - mean; q += (v[j][0] * v[j][0] + v[j][1] * v[j][1]) + (v[j][2] * v[j][2] + v[j][3] * v[j][3]); }
;     const float rstd = rsqrtf(wave_sum(q) * (1.f / DM) + LN_EPS);
.LBB0_1197:
	v_mov_b32_e32 v104, v38
	v_mov_b32_e32 v105, v42
	v_mov_b32_e32 v106, v39
	v_mov_b32_e32 v107, v43
	v_pk_add_f32 v[104:105], v[104:105], v[106:107]
	v_mov_b32_e32 v106, v40
	v_mov_b32_e32 v107, v44
	v_mov_b32_e32 v108, v41
	v_mov_b32_e32 v109, v45
	v_pk_add_f32 v[106:107], v[106:107], v[108:109]
	v_mov_b32_e32 v108, v34
	v_pk_add_f32 v[104:105], v[104:105], v[106:107]
	v_mov_b32_e32 v106, v35
	v_mov_b32_e32 v107, v36
	v_mov_b32_e32 v109, v37
	v_pk_add_f32 v[106:107], v[106:107], v[108:109]
	v_add_f32_e32 v9, 0, v105
	v_pk_add_f32 v[106:107], v[106:107], v[106:107] op_sel_hi:[0,1]
	v_add_f32_e32 v105, v104, v9
	v_add_f32_e32 v109, v30, v31
	v_add_f32_e32 v111, v32, v33
	v_mov_b32_e32 v108, v58
	v_mov_b32_e32 v110, v59
	v_mov_b32_e32 v106, v60
	v_mov_b32_e32 v104, v61
	v_pk_add_f32 v[108:109], v[108:109], v[110:111]
	v_pk_add_f32 v[104:105], v[106:107], v[104:105]
	v_mov_b32_e32 v106, v55
	v_pk_add_f32 v[104:105], v[108:109], v[104:105]
	v_mov_b32_e32 v107, v56
	v_mov_b32_e32 v108, v54
	v_mov_b32_e32 v109, v57
	v_pk_add_f32 v[106:107], v[106:107], v[108:109]
	v_pk_add_f32 v[104:105], v[104:105], v[104:105] op_sel_hi:[0,1]
	v_pk_add_f32 v[106:107], v[106:107], v[106:107] op_sel_hi:[0,1]
	v_add_f32_e32 v109, v50, v51
	v_add_f32_e32 v111, v52, v53
	v_mov_b32_e32 v108, v46
	v_mov_b32_e32 v110, v47
	v_mov_b32_e32 v106, v48
	v_mov_b32_e32 v104, v49
	v_pk_add_f32 v[108:109], v[108:109], v[110:111]
	v_pk_add_f32 v[104:105], v[106:107], v[104:105]
	s_ashr_i32 s9, s8, 31
	v_pk_add_f32 v[104:105], v[108:109], v[104:105]
	s_lshl_b64 s[8:9], s[8:9], 12
	v_add_f32_e32 v9, v104, v105
	s_waitcnt lgkmcnt(0)
	s_nop 1
	v_add_f32_dpp v9, v9, v9 quad_perm:[1,0,3,2] row_mask:0xf bank_mask:0xf
	s_waitcnt lgkmcnt(0)
	s_nop 1
	v_add_f32_dpp v9, v9, v9 quad_perm:[2,3,0,1] row_mask:0xf bank_mask:0xf
	ds_bpermute_b32 v11, v100, v9
	s_waitcnt lgkmcnt(0)
	v_add_f32_e32 v9, v9, v11
	ds_bpermute_b32 v11, v101, v9
	s_waitcnt lgkmcnt(0)
	v_add_f32_e32 v9, v9, v11
	ds_bpermute_b32 v11, v102, v9
	s_waitcnt lgkmcnt(0)
	v_add_f32_e32 v9, v9, v11
	ds_bpermute_b32 v11, v103, v9
	s_waitcnt lgkmcnt(0)
	v_add_f32_e32 v9, v9, v11
	v_fmamk_f32 v43, v9, 0xba000000, v43
	v_fmamk_f32 v39, v9, 0xba000000, v39
	v_fmamk_f32 v45, v9, 0xba000000, v45
	v_fmac_f32_e32 v42, 0xba000000, v9
	v_fmamk_f32 v41, v9, 0xba000000, v41
	v_fmac_f32_e32 v38, 0xba000000, v9
	v_mov_b32_e32 v106, v43
	v_mov_b32_e32 v107, v39
	v_fmamk_f32 v44, v9, 0xba000000, v44
	v_fmamk_f32 v40, v9, 0xba000000, v40
	v_mov_b32_e32 v104, v42
	v_mov_b32_e32 v105, v38
	v_pk_mul_f32 v[106:107], v[106:107], v[106:107]
	v_mov_b32_e32 v108, v45
	v_mov_b32_e32 v109, v41
	v_pk_fma_f32 v[104:105], v[104:105], v[104:105], v[106:107]
	v_mov_b32_e32 v106, v44
	v_mov_b32_e32 v107, v40
	v_pk_mul_f32 v[108:109], v[108:109], v[108:109]
	v_fmamk_f32 v37, v9, 0xba000000, v37
	v_pk_fma_f32 v[106:107], v[106:107], v[106:107], v[108:109]
	v_fmamk_f32 v36, v9, 0xba000000, v36
	v_pk_add_f32 v[104:105], v[104:105], v[106:107]
	v_fmamk_f32 v35, v9, 0xba000000, v35
	v_fmac_f32_e32 v34, 0xba000000, v9
	v_pk_add_f32 v[104:105], v[104:105], v[104:105] op_sel_hi:[0,1]
	v_pk_mul_f32 v[106:107], v[36:37], v[36:37]
	v_pk_mul_f32 v[108:109], v[34:35], v[34:35]
	v_fmac_f32_e32 v30, 0xba000000, v9
	v_pk_mov_b32 v[110:111], v[108:109], v[106:107] op_sel:[1,0]
	v_mov_b32_e32 v109, v107
	v_fmamk_f32 v32, v9, 0xba000000, v32
	v_fmamk_f32 v31, v9, 0xba000000, v31
	v_mul_f32_e32 v104, v30, v30
	v_pk_add_f32 v[106:107], v[110:111], v[108:109]
	v_fmamk_f32 v33, v9, 0xba000000, v33
	v_pk_fma_f32 v[108:109], v[30:31], v[30:31], v[104:105] op_sel_hi:[1,1,0]
	v_mul_f32_e32 v104, v32, v32
	v_pk_add_f32 v[106:107], v[106:107], v[106:107] op_sel_hi:[0,1]
	v_pk_fma_f32 v[110:111], v[32:33], v[32:33], v[104:105] op_sel_hi:[1,1,0]
	v_fmamk_f32 v61, v9, 0xba000000, v61
	v_fmamk_f32 v60, v9, 0xba000000, v60
	v_fmamk_f32 v59, v9, 0xba000000, v59
	v_fmac_f32_e32 v58, 0xba000000, v9
	v_mul_f32_e32 v108, v58, v58
	v_mul_f32_e32 v110, v59, v59
	v_mul_f32_e32 v106, v60, v60
	v_mul_f32_e32 v104, v61, v61
	v_pk_add_f32 v[108:109], v[108:109], v[110:111]
	v_pk_add_f32 v[104:105], v[106:107], v[104:105]
	v_fmamk_f32 v57, v9, 0xba000000, v57
	v_pk_add_f32 v[112:113], v[108:109], v[104:105]
	flat_load_dwordx4 v[104:107], v[62:63]
	flat_load_dwordx4 v[108:111], v[64:65]
	v_fmamk_f32 v56, v9, 0xba000000, v56
	v_fmamk_f32 v55, v9, 0xba000000, v55
	v_fmac_f32_e32 v54, 0xba000000, v9
	v_pk_add_f32 v[112:113], v[112:113], v[112:113] op_sel_hi:[0,1]
	v_pk_mul_f32 v[114:115], v[56:57], v[56:57]
	v_pk_mul_f32 v[116:117], v[54:55], v[54:55]
	v_fmac_f32_e32 v50, 0xba000000, v9
	v_pk_mov_b32 v[118:119], v[116:117], v[114:115] op_sel:[1,0]
	v_mov_b32_e32 v117, v115
	v_fmamk_f32 v52, v9, 0xba000000, v52
	v_fmamk_f32 v51, v9, 0xba000000, v51
	v_mul_f32_e32 v112, v50, v50
	v_pk_add_f32 v[114:115], v[118:119], v[116:117]
	v_fmamk_f32 v53, v9, 0xba000000, v53
	v_pk_fma_f32 v[116:117], v[50:51], v[50:51], v[112:113] op_sel_hi:[1,1,0]
	v_mul_f32_e32 v112, v52, v52
	v_pk_add_f32 v[114:115], v[114:115], v[114:115] op_sel_hi:[0,1]
	v_pk_fma_f32 v[118:119], v[52:53], v[52:53], v[112:113] op_sel_hi:[1,1,0]
	v_fmamk_f32 v49, v9, 0xba000000, v49
	v_fmamk_f32 v48, v9, 0xba000000, v48
	v_fmamk_f32 v47, v9, 0xba000000, v47
	v_fmac_f32_e32 v46, 0xba000000, v9
	v_mul_f32_e32 v116, v46, v46
	v_mul_f32_e32 v118, v47, v47
	v_mul_f32_e32 v114, v48, v48
	v_mul_f32_e32 v112, v49, v49
	v_pk_add_f32 v[116:117], v[116:117], v[118:119]
	v_pk_add_f32 v[112:113], v[114:115], v[112:113]
	s_nop 0
	v_pk_add_f32 v[112:113], v[116:117], v[112:113]
	s_nop 0
	v_add_f32_e32 v9, v112, v113
	s_waitcnt lgkmcnt(0)
; __device__ __forceinline__ unsigned cvt_pk_bf16(float lo, float hi) { unsigned r; asm volatile("v_cvt_pk_bf16_f32 %0, %1, %2" : "=v"(r) : "v"(lo), "v"(hi)); return r; }
; __device__ __forceinline__ void ln_apply(f32x4 (&v)[8], const float* __restrict__ g, const float* __restrict__ b, bf16_t* hb, float* fo, int lane) {
;     ...
;     const float rstd = rsqrtf(wave_sum(q) * (1.f / DM) + LN_EPS);
; #pragma unroll
;     for (int j = 0; j < 8; ++j) { const int c = (lane + 64 * j) * 4; const f32x4 gg = *(const f32x4*)(g + c), bb = *(const f32x4*)(b + c);
;         const f32x4 y = v[j] * rstd * gg + bb;
;         if (hb) { u32x2 w; w.x = cvt_pk_bf16(y[0], y[1]); w.y = cvt_pk_bf16(y[2], y[3]); *(u32x2*)(hb + c) = w; }
	s_nop 1
	v_add_f32_dpp v9, v9, v9 quad_perm:[1,0,3,2] row_mask:0xf bank_mask:0xf
	s_waitcnt lgkmcnt(0)
	s_nop 1
	v_add_f32_dpp v9, v9, v9 quad_perm:[2,3,0,1] row_mask:0xf bank_mask:0xf
	ds_bpermute_b32 v11, v100, v9
	s_waitcnt lgkmcnt(0)
	v_add_f32_e32 v9, v9, v11
	ds_bpermute_b32 v11, v101, v9
	s_waitcnt lgkmcnt(0)
	v_add_f32_e32 v9, v9, v11
	ds_bpermute_b32 v11, v102, v9
	s_waitcnt lgkmcnt(0)
	v_add_f32_e32 v9, v9, v11
	ds_bpermute_b32 v11, v103, v9
	s_waitcnt lgkmcnt(0)
	v_add_f32_e32 v9, v9, v11
	v_fmamk_f32 v9, v9, 0x3a000000, v1
	v_mul_f32_e32 v11, 0x4b800000, v9
	v_cmp_gt_f32_e32 vcc, s16, v9
	s_nop 1
	v_cndmask_b32_e32 v9, v9, v11, vcc
	v_rsq_f32_e32 v9, v9
	s_nop 0
	v_mul_f32_e32 v11, 0x45800000, v9
	v_cndmask_b32_e32 v112, v9, v11, vcc
	v_pk_mul_f32 v[114:115], v[42:43], v[112:113] op_sel_hi:[1,0]
	v_pk_mul_f32 v[116:117], v[44:45], v[112:113] op_sel_hi:[1,0]
	s_waitcnt vmcnt(0)
	v_pk_fma_f32 v[104:105], v[104:105], v[114:115], v[108:109]
	v_pk_fma_f32 v[106:107], v[106:107], v[116:117], v[110:111]
	v_cvt_pk_bf16_f32 v114, v104, v105
	v_pk_mul_f32 v[118:119], v[38:39], v[112:113] op_sel_hi:[1,0]
	v_cvt_pk_bf16_f32 v115, v106, v107
	flat_load_dwordx4 v[104:107], v[62:63] offset:1024
	flat_load_dwordx4 v[108:111], v[64:65] offset:1024
	v_pk_mul_f32 v[120:121], v[40:41], v[112:113] op_sel_hi:[1,0]
	v_lshl_add_u64 v[116:117], v[84:85], 0, s[8:9]
	flat_store_dwordx2 v[116:117], v[114:115]
	s_waitcnt vmcnt(0) lgkmcnt(0)
	v_pk_fma_f32 v[106:107], v[106:107], v[120:121], v[110:111]
	v_pk_fma_f32 v[104:105], v[104:105], v[118:119], v[108:109]
	v_pk_mul_f32 v[118:119], v[34:35], v[112:113] op_sel_hi:[1,0]
	v_cvt_pk_bf16_f32 v114, v104, v105
	v_cvt_pk_bf16_f32 v115, v106, v107
	flat_load_dwordx4 v[104:107], v[62:63] offset:2048
	flat_load_dwordx4 v[108:111], v[64:65] offset:2048
	v_pk_mul_f32 v[120:121], v[36:37], v[112:113] op_sel_hi:[1,0]
	flat_store_dwordx2 v[116:117], v[114:115] offset:512
	s_waitcnt vmcnt(0) lgkmcnt(0)
	v_pk_fma_f32 v[106:107], v[106:107], v[120:121], v[110:111]
	v_pk_fma_f32 v[104:105], v[104:105], v[118:119], v[108:109]
	v_pk_mul_f32 v[118:119], v[30:31], v[112:113] op_sel_hi:[1,0]
	v_cvt_pk_bf16_f32 v114, v104, v105
	v_cvt_pk_bf16_f32 v115, v106, v107
	flat_load_dwordx4 v[104:107], v[62:63] offset:3072
	flat_load_dwordx4 v[108:111], v[64:65] offset:3072
	v_pk_mul_f32 v[120:121], v[32:33], v[112:113] op_sel_hi:[1,0]
	flat_store_dwordx2 v[116:117], v[114:115] offset:1024
	s_waitcnt vmcnt(0) lgkmcnt(0)
	v_pk_fma_f32 v[106:107], v[106:107], v[120:121], v[110:111]
	v_pk_fma_f32 v[104:105], v[104:105], v[118:119], v[108:109]
	v_pk_mul_f32 v[118:119], v[58:59], v[112:113] op_sel_hi:[1,0]
	v_cvt_pk_bf16_f32 v114, v104, v105
	v_cvt_pk_bf16_f32 v115, v106, v107
	flat_load_dwordx4 v[104:107], v[66:67]
	flat_load_dwordx4 v[108:111], v[68:69]
	v_pk_mul_f32 v[120:121], v[60:61], v[112:113] op_sel_hi:[1,0]
	flat_store_dwordx2 v[116:117], v[114:115] offset:1536
	s_waitcnt vmcnt(0) lgkmcnt(0)
	v_pk_fma_f32 v[106:107], v[106:107], v[120:121], v[110:111]
	v_pk_fma_f32 v[104:105], v[104:105], v[118:119], v[108:109]
	v_pk_mul_f32 v[118:119], v[54:55], v[112:113] op_sel_hi:[1,0]
	v_cvt_pk_bf16_f32 v114, v104, v105
	v_cvt_pk_bf16_f32 v115, v106, v107
	flat_load_dwordx4 v[104:107], v[70:71]
	flat_load_dwordx4 v[108:111], v[72:73]
	v_pk_mul_f32 v[120:121], v[56:57], v[112:113] op_sel_hi:[1,0]
	flat_store_dwordx2 v[116:117], v[114:115] offset:2048
	s_waitcnt vmcnt(0) lgkmcnt(0)
	v_pk_fma_f32 v[106:107], v[106:107], v[120:121], v[110:111]
	v_pk_fma_f32 v[104:105], v[104:105], v[118:119], v[108:109]
	v_pk_mul_f32 v[118:119], v[50:51], v[112:113] op_sel_hi:[1,0]
	v_cvt_pk_bf16_f32 v114, v104, v105
	v_cvt_pk_bf16_f32 v115, v106, v107
	flat_load_dwordx4 v[104:107], v[74:75]
	flat_load_dwordx4 v[108:111], v[76:77]
	v_pk_mul_f32 v[120:121], v[52:53], v[112:113] op_sel_hi:[1,0]
	flat_store_dwordx2 v[116:117], v[114:115] offset:2560
	s_waitcnt vmcnt(0) lgkmcnt(0)
	v_pk_fma_f32 v[106:107], v[120:121], v[106:107], v[110:111]
	v_pk_fma_f32 v[104:105], v[118:119], v[104:105], v[108:109]
	v_pk_mul_f32 v[118:119], v[46:47], v[112:113] op_sel_hi:[1,0]
	v_cvt_pk_bf16_f32 v114, v104, v105
	v_cvt_pk_bf16_f32 v115, v106, v107
	flat_load_dwordx4 v[104:107], v[80:81]
	flat_load_dwordx4 v[108:111], v[82:83]
	v_pk_mul_f32 v[112:113], v[48:49], v[112:113] op_sel_hi:[1,0]
	flat_store_dwordx2 v[116:117], v[114:115] offset:3072
	s_waitcnt vmcnt(0) lgkmcnt(0)
	v_pk_fma_f32 v[104:105], v[118:119], v[104:105], v[108:109]
	v_pk_fma_f32 v[106:107], v[112:113], v[106:107], v[110:111]
	v_cvt_pk_bf16_f32 v104, v104, v105
	s_nop 0
	v_cvt_pk_bf16_f32 v105, v106, v107
	flat_store_dwordx2 v[116:117], v[104:105] offset:3584

; __device__ __forceinline__ float wave_sum(float v) {
; #pragma unroll
;     for (int o = 1; o < 64; o <<= 1) v += __shfl_xor(v, o);
;     return v;
; __device__ __forceinline__ void ln_apply(f32x4 (&v)[8], const float* __restrict__ g, const float* __restrict__ b, bf16_t* hb, float* fo, int lane) {
;     float s = 0.f;
; #pragma unroll
;     for (int j = 0; j < 8; ++j) s += (v[j][0] + v[j][1]) + (v[j][2] + v[j][3]);
;     const float mean = wave_sum(s) * (1.f / DM); float q = 0.f;
; #pragma unroll
;     for (int j = 0; j < 8; ++j) { v[j] = v[j] - mean; q += (v[j][0] * v[j][0] + v[j][1] * v[j][1]) + (v[j][2] * v[j][2] + v[j][3] * v[j][3]); }
;     const float rstd = rsqrtf(wave_sum(q) * (1.f / DM) + LN_EPS);
.LBB0_1201:
	v_pk_add_f32 v[104:105], v[86:87], v[2:3]
	v_pk_add_f32 v[106:107], v[88:89], v[4:5]
	v_add_f32_e32 v11, v26, v27
	v_pk_add_f32 v[104:105], v[104:105], v[106:107]
	v_add_f32_e32 v19, v22, v23
	v_add_f32_e32 v9, 0, v105
	v_add_f32_e32 v93, v104, v9
	v_pk_add_f32 v[104:105], v[90:91], v[6:7]
	v_add_f32_e32 v9, v28, v29
	v_pk_add_f32 v[104:105], v[104:105], v[104:105] op_sel_hi:[0,1]
	v_mov_b32_e32 v13, v105
	v_pk_add_f32 v[106:107], v[10:11], v[8:9]
	v_pk_add_f32 v[104:105], v[12:13], v[92:93]
	v_add_f32_e32 v17, v24, v25
	v_pk_add_f32 v[104:105], v[106:107], v[104:105]
	v_pk_add_f32 v[106:107], v[94:95], v[14:15]
	v_pk_add_f32 v[104:105], v[104:105], v[104:105] op_sel_hi:[0,1]
	v_pk_add_f32 v[106:107], v[106:107], v[106:107] op_sel_hi:[0,1]
	v_mov_b32_e32 v21, v107
	v_mov_b32_e32 v97, v105
	v_pk_add_f32 v[108:109], v[18:19], v[16:17]
	v_pk_add_f32 v[104:105], v[20:21], v[96:97]
	s_ashr_i32 s7, s6, 31
	v_pk_add_f32 v[104:105], v[108:109], v[104:105]
	s_lshl_b64 s[10:11], s[6:7], 12
	v_add_f32_e32 v9, v104, v105
	s_cmpk_gt_i32 s8, 0x400f
	s_waitcnt lgkmcnt(0)
	s_nop 1
	v_add_f32_dpp v9, v9, v9 quad_perm:[1,0,3,2] row_mask:0xf bank_mask:0xf
	s_waitcnt lgkmcnt(0)
	s_nop 1
	v_add_f32_dpp v9, v9, v9 quad_perm:[2,3,0,1] row_mask:0xf bank_mask:0xf
	ds_bpermute_b32 v11, v100, v9
	s_waitcnt lgkmcnt(0)
	v_add_f32_e32 v9, v9, v11
	ds_bpermute_b32 v11, v101, v9
	s_waitcnt lgkmcnt(0)
	v_add_f32_e32 v9, v9, v11
	ds_bpermute_b32 v11, v102, v9
	s_waitcnt lgkmcnt(0)
	v_add_f32_e32 v9, v9, v11
	ds_bpermute_b32 v11, v103, v9
	s_waitcnt lgkmcnt(0)
	v_add_f32_e32 v9, v9, v11
	v_fmac_f32_e32 v3, 0xba000000, v9
	v_fmac_f32_e32 v2, 0xba000000, v9
	v_fmac_f32_e32 v87, 0xba000000, v9
	v_fmac_f32_e32 v86, 0xba000000, v9
	v_mov_b32_e32 v106, v3
	v_mov_b32_e32 v107, v2
	v_fmac_f32_e32 v5, 0xba000000, v9
	v_fmac_f32_e32 v4, 0xba000000, v9
	v_mov_b32_e32 v104, v87
	v_mov_b32_e32 v105, v86
	v_pk_mul_f32 v[106:107], v[106:107], v[106:107]
	v_fmac_f32_e32 v89, 0xba000000, v9
	v_fmac_f32_e32 v88, 0xba000000, v9
	v_pk_fma_f32 v[104:105], v[104:105], v[104:105], v[106:107]
	v_mov_b32_e32 v106, v5
	v_mov_b32_e32 v107, v4
	v_mov_b32_e32 v108, v89
	v_mov_b32_e32 v109, v88
	v_pk_mul_f32 v[106:107], v[106:107], v[106:107]
	v_fmac_f32_e32 v7, 0xba000000, v9
	v_pk_fma_f32 v[106:107], v[108:109], v[108:109], v[106:107]
	v_fmac_f32_e32 v91, 0xba000000, v9
	v_fmac_f32_e32 v90, 0xba000000, v9
	v_fmac_f32_e32 v6, 0xba000000, v9
	v_pk_add_f32 v[104:105], v[104:105], v[106:107]
	v_mov_b32_e32 v112, v91
	v_mov_b32_e32 v113, v7
	v_mov_b32_e32 v114, v6
	v_mov_b32_e32 v115, v90
	v_pk_add_f32 v[104:105], v[104:105], v[104:105] op_sel_hi:[0,1]
	v_pk_mul_f32 v[106:107], v[112:113], v[112:113]
	v_pk_mul_f32 v[108:109], v[114:115], v[114:115]
	v_fmac_f32_e32 v26, 0xba000000, v9
	v_pk_mov_b32 v[110:111], v[108:109], v[106:107] op_sel:[1,0]
	v_mov_b32_e32 v109, v107
	v_fmac_f32_e32 v28, 0xba000000, v9
	v_fmac_f32_e32 v27, 0xba000000, v9
	v_mul_f32_e32 v104, v26, v26
	v_pk_add_f32 v[106:107], v[110:111], v[108:109]
	v_fmac_f32_e32 v29, 0xba000000, v9
	v_pk_fma_f32 v[108:109], v[26:27], v[26:27], v[104:105] op_sel_hi:[1,1,0]
	v_mul_f32_e32 v104, v28, v28
	v_pk_add_f32 v[106:107], v[106:107], v[106:107] op_sel_hi:[0,1]
	v_pk_fma_f32 v[110:111], v[28:29], v[28:29], v[104:105] op_sel_hi:[1,1,0]
	v_fmac_f32_e32 v92, 0xba000000, v9
	v_fmac_f32_e32 v12, 0xba000000, v9
	v_fmac_f32_e32 v8, 0xba000000, v9
	v_fmac_f32_e32 v10, 0xba000000, v9
	v_mul_f32_e32 v108, v10, v10
	v_mul_f32_e32 v110, v8, v8
	v_mul_f32_e32 v106, v12, v12
	v_mul_f32_e32 v104, v92, v92
	v_pk_add_f32 v[108:109], v[108:109], v[110:111]
	v_pk_add_f32 v[104:105], v[106:107], v[104:105]
	v_fmac_f32_e32 v15, 0xba000000, v9
	v_pk_add_f32 v[104:105], v[108:109], v[104:105]
	v_fmac_f32_e32 v95, 0xba000000, v9
	v_pk_add_f32 v[116:117], v[104:105], v[104:105] op_sel_hi:[0,1]
	flat_load_dwordx4 v[104:107], v[62:63]
	flat_load_dwordx4 v[108:111], v[64:65]
	v_fmac_f32_e32 v94, 0xba000000, v9
	v_fmac_f32_e32 v14, 0xba000000, v9
	v_mov_b32_e32 v118, v95
	v_mov_b32_e32 v119, v15
	v_mov_b32_e32 v122, v14
	v_mov_b32_e32 v123, v94
	v_pk_mul_f32 v[120:121], v[118:119], v[118:119]
	v_pk_mul_f32 v[124:125], v[122:123], v[122:123]
	v_fmac_f32_e32 v22, 0xba000000, v9
	v_pk_mov_b32 v[126:127], v[124:125], v[120:121] op_sel:[1,0]
	v_mov_b32_e32 v125, v121
	v_fmac_f32_e32 v24, 0xba000000, v9
	v_fmac_f32_e32 v23, 0xba000000, v9
	v_mul_f32_e32 v116, v22, v22
	v_pk_add_f32 v[120:121], v[126:127], v[124:125]
	v_fmac_f32_e32 v25, 0xba000000, v9
	v_pk_fma_f32 v[124:125], v[22:23], v[22:23], v[116:117] op_sel_hi:[1,1,0]
	v_mul_f32_e32 v116, v24, v24
	v_pk_add_f32 v[120:121], v[120:121], v[120:121] op_sel_hi:[0,1]
	v_pk_fma_f32 v[126:127], v[24:25], v[24:25], v[116:117] op_sel_hi:[1,1,0]
	v_fmac_f32_e32 v96, 0xba000000, v9
	v_fmac_f32_e32 v20, 0xba000000, v9
	v_fmac_f32_e32 v16, 0xba000000, v9
	v_fmac_f32_e32 v18, 0xba000000, v9
	v_mul_f32_e32 v124, v18, v18
	v_mul_f32_e32 v126, v16, v16
	v_mul_f32_e32 v120, v20, v20
	v_mul_f32_e32 v116, v96, v96
	v_pk_add_f32 v[124:125], v[124:125], v[126:127]
	v_pk_add_f32 v[116:117], v[120:121], v[116:117]
	v_mov_b32_e32 v120, v89
	v_pk_add_f32 v[116:117], v[124:125], v[116:117]
	v_mov_b32_e32 v121, v5
	v_add_f32_e32 v9, v116, v117
	v_mov_b32_e32 v116, v87
	v_mov_b32_e32 v117, v3
	v_mov_b32_e32 v126, v86
	v_mov_b32_e32 v127, v2
	s_waitcnt lgkmcnt(0)
	s_nop 1
	v_add_f32_dpp v9, v9, v9 quad_perm:[1,0,3,2] row_mask:0xf bank_mask:0xf
	v_mov_b32_e32 v128, v88
	v_mov_b32_e32 v129, v4
	v_mov_b32_e32 v13, v92
	v_mov_b32_e32 v19, v16
	s_waitcnt lgkmcnt(0)
; __device__ __forceinline__ unsigned cvt_pk_bf16(float lo, float hi) { unsigned r; asm volatile("v_cvt_pk_bf16_f32 %0, %1, %2" : "=v"(r) : "v"(lo), "v"(hi)); return r; }
; __device__ __forceinline__ void ln_apply(f32x4 (&v)[8], const float* __restrict__ g, const float* __restrict__ b, bf16_t* hb, float* fo, int lane) {
;     ...
;     const float rstd = rsqrtf(wave_sum(q) * (1.f / DM) + LN_EPS);
; #pragma unroll
;     for (int j = 0; j < 8; ++j) { const int c = (lane + 64 * j) * 4; const f32x4 gg = *(const f32x4*)(g + c), bb = *(const f32x4*)(b + c);
;         const f32x4 y = v[j] * rstd * gg + bb;
;         if (hb) { u32x2 w; w.x = cvt_pk_bf16(y[0], y[1]); w.y = cvt_pk_bf16(y[2], y[3]); *(u32x2*)(hb + c) = w; }
	s_nop 1
	v_add_f32_dpp v9, v9, v9 quad_perm:[2,3,0,1] row_mask:0xf bank_mask:0xf
	ds_bpermute_b32 v11, v100, v9
	v_mov_b32_e32 v21, v96
	s_waitcnt lgkmcnt(0)
	v_add_f32_e32 v9, v9, v11
	ds_bpermute_b32 v11, v101, v9
	s_waitcnt lgkmcnt(0)
	v_add_f32_e32 v9, v9, v11
	ds_bpermute_b32 v11, v102, v9
	s_waitcnt lgkmcnt(0)
	v_add_f32_e32 v9, v9, v11
	ds_bpermute_b32 v11, v103, v9
	s_waitcnt lgkmcnt(0)
	v_add_f32_e32 v9, v9, v11
	v_fmamk_f32 v9, v9, 0x3a000000, v1
	v_mul_f32_e32 v11, 0x4b800000, v9
	v_cmp_gt_f32_e32 vcc, s16, v9
	s_nop 1
	v_cndmask_b32_e32 v9, v9, v11, vcc
	v_rsq_f32_e32 v9, v9
	s_nop 0
	v_mul_f32_e32 v11, 0x45800000, v9
	v_cndmask_b32_e32 v124, v9, v11, vcc
	v_pk_mul_f32 v[116:117], v[116:117], v[124:125] op_sel_hi:[1,0]
	v_pk_mul_f32 v[120:121], v[120:121], v[124:125] op_sel_hi:[1,0]
	s_waitcnt vmcnt(0)
	v_pk_fma_f32 v[104:105], v[104:105], v[116:117], v[108:109]
	v_pk_fma_f32 v[106:107], v[106:107], v[120:121], v[110:111]
	v_cvt_pk_bf16_f32 v116, v104, v105
	v_pk_mul_f32 v[126:127], v[126:127], v[124:125] op_sel_hi:[1,0]
	v_cvt_pk_bf16_f32 v117, v106, v107
	flat_load_dwordx4 v[104:107], v[62:63] offset:1024
	flat_load_dwordx4 v[108:111], v[64:65] offset:1024
	v_pk_mul_f32 v[128:129], v[128:129], v[124:125] op_sel_hi:[1,0]
	v_lshl_add_u64 v[120:121], v[84:85], 0, s[10:11]
	flat_store_dwordx2 v[120:121], v[116:117]
	v_pk_mul_f32 v[114:115], v[114:115], v[124:125] op_sel_hi:[1,0]
	v_pk_mul_f32 v[112:113], v[112:113], v[124:125] op_sel_hi:[1,0]
	v_mov_b32_e32 v11, v8
	s_mov_b64 s[10:11], -1
	s_waitcnt vmcnt(0) lgkmcnt(0)
	v_pk_fma_f32 v[106:107], v[106:107], v[128:129], v[110:111]
	v_pk_fma_f32 v[104:105], v[104:105], v[126:127], v[108:109]
	s_nop 0
	v_cvt_pk_bf16_f32 v116, v104, v105
	v_cvt_pk_bf16_f32 v117, v106, v107
	flat_load_dwordx4 v[104:107], v[62:63] offset:2048
	flat_load_dwordx4 v[108:111], v[64:65] offset:2048
	s_waitcnt vmcnt(0) lgkmcnt(0)
	v_pk_fma_f32 v[106:107], v[106:107], v[112:113], v[110:111]
	v_pk_fma_f32 v[104:105], v[104:105], v[114:115], v[108:109]
	flat_store_dwordx2 v[120:121], v[116:117] offset:512
	v_cvt_pk_bf16_f32 v112, v104, v105
	v_cvt_pk_bf16_f32 v113, v106, v107
	flat_load_dwordx4 v[104:107], v[62:63] offset:3072
	flat_load_dwordx4 v[108:111], v[64:65] offset:3072
	v_pk_mul_f32 v[114:115], v[26:27], v[124:125] op_sel_hi:[1,0]
	v_pk_mul_f32 v[116:117], v[28:29], v[124:125] op_sel_hi:[1,0]
	flat_store_dwordx2 v[120:121], v[112:113] offset:1024
	s_waitcnt vmcnt(0) lgkmcnt(0)
	v_pk_fma_f32 v[106:107], v[106:107], v[116:117], v[110:111]
	v_pk_fma_f32 v[104:105], v[104:105], v[114:115], v[108:109]
	v_pk_mul_f32 v[114:115], v[10:11], v[124:125] op_sel_hi:[1,0]
	v_cvt_pk_bf16_f32 v112, v104, v105
	v_cvt_pk_bf16_f32 v113, v106, v107
	flat_load_dwordx4 v[104:107], v[66:67]
	flat_load_dwordx4 v[108:111], v[68:69]
	v_pk_mul_f32 v[116:117], v[12:13], v[124:125] op_sel_hi:[1,0]
	flat_store_dwordx2 v[120:121], v[112:113] offset:1536
	s_waitcnt vmcnt(0) lgkmcnt(0)
	v_pk_fma_f32 v[106:107], v[106:107], v[116:117], v[110:111]
	v_pk_fma_f32 v[104:105], v[104:105], v[114:115], v[108:109]
	v_pk_mul_f32 v[114:115], v[122:123], v[124:125] op_sel_hi:[1,0]
	v_cvt_pk_bf16_f32 v112, v104, v105
	v_cvt_pk_bf16_f32 v113, v106, v107
	flat_load_dwordx4 v[104:107], v[70:71]
	flat_load_dwordx4 v[108:111], v[72:73]
	v_pk_mul_f32 v[116:117], v[118:119], v[124:125] op_sel_hi:[1,0]
	flat_store_dwordx2 v[120:121], v[112:113] offset:2048
	s_waitcnt vmcnt(0) lgkmcnt(0)
	v_pk_fma_f32 v[106:107], v[106:107], v[116:117], v[110:111]
	v_pk_fma_f32 v[104:105], v[104:105], v[114:115], v[108:109]
	v_pk_mul_f32 v[114:115], v[22:23], v[124:125] op_sel_hi:[1,0]
	v_cvt_pk_bf16_f32 v112, v104, v105
	v_cvt_pk_bf16_f32 v113, v106, v107
	flat_load_dwordx4 v[104:107], v[74:75]
	flat_load_dwordx4 v[108:111], v[76:77]
	v_pk_mul_f32 v[116:117], v[24:25], v[124:125] op_sel_hi:[1,0]
	flat_store_dwordx2 v[120:121], v[112:113] offset:2560
	s_waitcnt vmcnt(0) lgkmcnt(0)
	v_pk_fma_f32 v[106:107], v[116:117], v[106:107], v[110:111]
	v_pk_fma_f32 v[104:105], v[114:115], v[104:105], v[108:109]
	v_pk_mul_f32 v[114:115], v[18:19], v[124:125] op_sel_hi:[1,0]
	v_cvt_pk_bf16_f32 v112, v104, v105
	v_cvt_pk_bf16_f32 v113, v106, v107
	flat_load_dwordx4 v[104:107], v[80:81]
	flat_load_dwordx4 v[108:111], v[82:83]
	v_pk_mul_f32 v[116:117], v[20:21], v[124:125] op_sel_hi:[1,0]
	flat_store_dwordx2 v[120:121], v[112:113] offset:3072
	s_waitcnt vmcnt(0) lgkmcnt(0)
	v_pk_fma_f32 v[104:105], v[114:115], v[104:105], v[108:109]
	v_pk_fma_f32 v[106:107], v[116:117], v[106:107], v[110:111]
	v_cvt_pk_bf16_f32 v104, v104, v105
	s_nop 0
	v_cvt_pk_bf16_f32 v105, v106, v107
	flat_store_dwordx2 v[120:121], v[104:105] offset:3584
	s_cbranch_scc1 .LBB0_1198
	s_add_i32 s12, s8, s3
	s_cmpk_gt_i32 s12, 0x400f
	s_cselect_b64 s[10:11], -1, 0
	s_and_b64 vcc, exec, s[10:11]
	s_cbranch_vccnz .LBB0_1197
	s_ashr_i32 s13, s12, 31
	s_lshl_b64 s[6:7], s[12:13], 13
	v_lshl_add_u64 v[86:87], v[78:79], 0, s[6:7]
	flat_load_dwordx4 v[2:5], v[86:87]
	flat_load_dwordx4 v[90:93], v[86:87] offset:1024
	flat_load_dwordx4 v[6:9], v[86:87] offset:2048
	v_add_co_u32_e32 v88, vcc, 0x1000, v86
	s_mov_b32 s6, s12
	s_nop 0
	v_addc_co_u32_e32 v89, vcc, 0, v87, vcc
	flat_load_dwordx4 v[10:13], v[88:89]
	flat_load_dwordx4 v[14:17], v[88:89] offset:1024
	flat_load_dwordx4 v[18:21], v[88:89] offset:3072
	flat_load_dwordx4 v[22:25], v[88:89] offset:2048
	flat_load_dwordx4 v[26:29], v[86:87] offset:3072
	s_waitcnt vmcnt(0) lgkmcnt(0)
	v_mov_b32_e32 v87, v2
	v_mov_b32_e32 v89, v4
	v_mov_b32_e32 v86, v90
	v_mov_b32_e32 v2, v91
	v_mov_b32_e32 v88, v92
	v_mov_b32_e32 v4, v93
	v_mov_b32_e32 v90, v7
	v_mov_b32_e32 v91, v8
	v_mov_b32_e32 v7, v9
	v_mov_b32_e32 v8, v11
	v_mov_b32_e32 v92, v13
	v_mov_b32_e32 v94, v15
	v_mov_b32_e32 v95, v16
	v_mov_b32_e32 v15, v17
	v_mov_b32_e32 v16, v19
	v_mov_b32_e32 v96, v21
	s_branch .LBB0_1197

; __device__ __forceinline__ float wave_sum(float v) {
; #pragma unroll
;     for (int o = 1; o < 64; o <<= 1) v += __shfl_xor(v, o);
;     return v;
; __device__ __forceinline__ void ln_apply(f32x4 (&v)[8], const float* __restrict__ g, const float* __restrict__ b, bf16_t* hb, float* fo, int lane) {
;     float s = 0.f;
; #pragma unroll
;     for (int j = 0; j < 8; ++j) s += (v[j][0] + v[j][1]) + (v[j][2] + v[j][3]);
;     const float mean = wave_sum(s) * (1.f / DM); float q = 0.f;
; #pragma unroll
;     for (int j = 0; j < 8; ++j) { v[j] = v[j] - mean; q += (v[j][0] * v[j][0] + v[j][1] * v[j][1]) + (v[j][2] * v[j][2] + v[j][3] * v[j][3]); }
;     const float rstd = rsqrtf(wave_sum(q) * (1.f / DM) + LN_EPS);
.LBB0_2625:
	v_mov_b32_e32 v116, v38
	v_mov_b32_e32 v117, v42
	v_mov_b32_e32 v118, v39
	v_mov_b32_e32 v119, v43
	v_pk_add_f32 v[116:117], v[116:117], v[118:119]
	v_mov_b32_e32 v118, v40
	v_mov_b32_e32 v119, v44
	v_mov_b32_e32 v120, v41
	v_mov_b32_e32 v121, v45
	v_pk_add_f32 v[118:119], v[118:119], v[120:121]
	v_mov_b32_e32 v120, v34
	v_pk_add_f32 v[116:117], v[116:117], v[118:119]
	v_mov_b32_e32 v118, v35
	v_mov_b32_e32 v119, v36
	v_mov_b32_e32 v121, v37
	v_pk_add_f32 v[118:119], v[118:119], v[120:121]
	v_add_f32_e32 v9, 0, v117
	v_pk_add_f32 v[118:119], v[118:119], v[118:119] op_sel_hi:[0,1]
	v_add_f32_e32 v117, v116, v9
	v_add_f32_e32 v121, v30, v31
	v_add_f32_e32 v123, v32, v33
	v_mov_b32_e32 v120, v58
	v_mov_b32_e32 v122, v59
	v_mov_b32_e32 v118, v60
	v_mov_b32_e32 v116, v61
	v_pk_add_f32 v[120:121], v[120:121], v[122:123]
	v_pk_add_f32 v[116:117], v[118:119], v[116:117]
	v_mov_b32_e32 v118, v55
	v_pk_add_f32 v[116:117], v[120:121], v[116:117]
	v_mov_b32_e32 v119, v56
	v_mov_b32_e32 v120, v54
	v_mov_b32_e32 v121, v57
	v_pk_add_f32 v[118:119], v[118:119], v[120:121]
	v_pk_add_f32 v[116:117], v[116:117], v[116:117] op_sel_hi:[0,1]
	v_pk_add_f32 v[118:119], v[118:119], v[118:119] op_sel_hi:[0,1]
	v_add_f32_e32 v121, v50, v51
	v_add_f32_e32 v123, v52, v53
	v_mov_b32_e32 v120, v46
	v_mov_b32_e32 v122, v47
	v_mov_b32_e32 v118, v48
	v_mov_b32_e32 v116, v49
	v_pk_add_f32 v[120:121], v[120:121], v[122:123]
	v_pk_add_f32 v[116:117], v[118:119], v[116:117]
	s_ashr_i32 s11, s10, 31
	v_pk_add_f32 v[116:117], v[120:121], v[116:117]
	s_lshl_b64 s[10:11], s[10:11], 12
	v_add_f32_e32 v9, v116, v117
	s_waitcnt lgkmcnt(0)
	s_nop 1
	v_add_f32_dpp v9, v9, v9 quad_perm:[1,0,3,2] row_mask:0xf bank_mask:0xf
	s_waitcnt lgkmcnt(0)
	s_nop 1
	v_add_f32_dpp v9, v9, v9 quad_perm:[2,3,0,1] row_mask:0xf bank_mask:0xf
	ds_bpermute_b32 v11, v112, v9
	s_waitcnt lgkmcnt(0)
	v_add_f32_e32 v9, v9, v11
	ds_bpermute_b32 v11, v113, v9
	s_waitcnt lgkmcnt(0)
	v_add_f32_e32 v9, v9, v11
	ds_bpermute_b32 v11, v114, v9
	s_waitcnt lgkmcnt(0)
	v_add_f32_e32 v9, v9, v11
	ds_bpermute_b32 v11, v115, v9
	s_waitcnt lgkmcnt(0)
	v_add_f32_e32 v9, v9, v11
	v_fmamk_f32 v43, v9, 0xba000000, v43
	v_fmamk_f32 v39, v9, 0xba000000, v39
	v_fmamk_f32 v45, v9, 0xba000000, v45
	v_fmac_f32_e32 v42, 0xba000000, v9
	v_fmamk_f32 v41, v9, 0xba000000, v41
	v_fmac_f32_e32 v38, 0xba000000, v9
	v_mov_b32_e32 v118, v43
	v_mov_b32_e32 v119, v39
	v_fmamk_f32 v44, v9, 0xba000000, v44
	v_fmamk_f32 v40, v9, 0xba000000, v40
	v_mov_b32_e32 v116, v42
	v_mov_b32_e32 v117, v38
	v_pk_mul_f32 v[118:119], v[118:119], v[118:119]
	v_mov_b32_e32 v120, v45
	v_mov_b32_e32 v121, v41
	v_pk_fma_f32 v[116:117], v[116:117], v[116:117], v[118:119]
	v_mov_b32_e32 v118, v44
	v_mov_b32_e32 v119, v40
	v_pk_mul_f32 v[120:121], v[120:121], v[120:121]
	v_fmamk_f32 v37, v9, 0xba000000, v37
	v_pk_fma_f32 v[118:119], v[118:119], v[118:119], v[120:121]
	v_fmamk_f32 v36, v9, 0xba000000, v36
	v_pk_add_f32 v[116:117], v[116:117], v[118:119]
	v_fmamk_f32 v35, v9, 0xba000000, v35
	v_fmac_f32_e32 v34, 0xba000000, v9
	v_pk_add_f32 v[116:117], v[116:117], v[116:117] op_sel_hi:[0,1]
	v_pk_mul_f32 v[118:119], v[36:37], v[36:37]
	v_pk_mul_f32 v[120:121], v[34:35], v[34:35]
	v_fmac_f32_e32 v30, 0xba000000, v9
	v_pk_mov_b32 v[122:123], v[120:121], v[118:119] op_sel:[1,0]
	v_mov_b32_e32 v121, v119
	v_fmamk_f32 v32, v9, 0xba000000, v32
	v_fmamk_f32 v31, v9, 0xba000000, v31
	v_mul_f32_e32 v116, v30, v30
	v_pk_add_f32 v[118:119], v[122:123], v[120:121]
	v_fmamk_f32 v33, v9, 0xba000000, v33
	v_pk_fma_f32 v[120:121], v[30:31], v[30:31], v[116:117] op_sel_hi:[1,1,0]
	v_mul_f32_e32 v116, v32, v32
	v_pk_add_f32 v[118:119], v[118:119], v[118:119] op_sel_hi:[0,1]
	v_pk_fma_f32 v[122:123], v[32:33], v[32:33], v[116:117] op_sel_hi:[1,1,0]
	v_fmamk_f32 v61, v9, 0xba000000, v61
	v_fmamk_f32 v60, v9, 0xba000000, v60
	v_fmamk_f32 v59, v9, 0xba000000, v59
	v_fmac_f32_e32 v58, 0xba000000, v9
	v_mul_f32_e32 v120, v58, v58
	v_mul_f32_e32 v122, v59, v59
	v_mul_f32_e32 v118, v60, v60
	v_mul_f32_e32 v116, v61, v61
	v_pk_add_f32 v[120:121], v[120:121], v[122:123]
	v_pk_add_f32 v[116:117], v[118:119], v[116:117]
	v_fmamk_f32 v57, v9, 0xba000000, v57
	v_pk_add_f32 v[124:125], v[120:121], v[116:117]
	flat_load_dwordx4 v[116:119], v[78:79]
	flat_load_dwordx4 v[120:123], v[64:65]
	v_fmamk_f32 v56, v9, 0xba000000, v56
	v_fmamk_f32 v55, v9, 0xba000000, v55
	v_fmac_f32_e32 v54, 0xba000000, v9
	v_pk_add_f32 v[124:125], v[124:125], v[124:125] op_sel_hi:[0,1]
	v_pk_mul_f32 v[126:127], v[56:57], v[56:57]
	v_pk_mul_f32 v[128:129], v[54:55], v[54:55]
	v_fmac_f32_e32 v50, 0xba000000, v9
	v_pk_mov_b32 v[130:131], v[128:129], v[126:127] op_sel:[1,0]
	v_mov_b32_e32 v129, v127
	v_fmamk_f32 v52, v9, 0xba000000, v52
	v_fmamk_f32 v51, v9, 0xba000000, v51
	v_mul_f32_e32 v124, v50, v50
	v_pk_add_f32 v[126:127], v[130:131], v[128:129]
	v_fmamk_f32 v53, v9, 0xba000000, v53
	v_pk_fma_f32 v[128:129], v[50:51], v[50:51], v[124:125] op_sel_hi:[1,1,0]
	v_mul_f32_e32 v124, v52, v52
	v_pk_add_f32 v[126:127], v[126:127], v[126:127] op_sel_hi:[0,1]
	v_pk_fma_f32 v[130:131], v[52:53], v[52:53], v[124:125] op_sel_hi:[1,1,0]
	v_fmamk_f32 v49, v9, 0xba000000, v49
	v_fmamk_f32 v48, v9, 0xba000000, v48
	v_fmamk_f32 v47, v9, 0xba000000, v47
	v_fmac_f32_e32 v46, 0xba000000, v9
	v_mul_f32_e32 v128, v46, v46
	v_mul_f32_e32 v130, v47, v47
	v_mul_f32_e32 v126, v48, v48
	v_mul_f32_e32 v124, v49, v49
	v_pk_add_f32 v[128:129], v[128:129], v[130:131]
	v_pk_add_f32 v[124:125], v[126:127], v[124:125]
	s_nop 0
	v_pk_add_f32 v[124:125], v[128:129], v[124:125]
	s_nop 0
	v_add_f32_e32 v9, v124, v125
	s_waitcnt lgkmcnt(0)
; __device__ __forceinline__ unsigned cvt_pk_bf16(float lo, float hi) { unsigned r; asm volatile("v_cvt_pk_bf16_f32 %0, %1, %2" : "=v"(r) : "v"(lo), "v"(hi)); return r; }
; __device__ __forceinline__ void ln_apply(f32x4 (&v)[8], const float* __restrict__ g, const float* __restrict__ b, bf16_t* hb, float* fo, int lane) {
;     ...
;     const float rstd = rsqrtf(wave_sum(q) * (1.f / DM) + LN_EPS);
; #pragma unroll
;     for (int j = 0; j < 8; ++j) { const int c = (lane + 64 * j) * 4; const f32x4 gg = *(const f32x4*)(g + c), bb = *(const f32x4*)(b + c);
;         const f32x4 y = v[j] * rstd * gg + bb;
;         if (hb) { u32x2 w; w.x = cvt_pk_bf16(y[0], y[1]); w.y = cvt_pk_bf16(y[2], y[3]); *(u32x2*)(hb + c) = w; }
	s_nop 1
	v_add_f32_dpp v9, v9, v9 quad_perm:[1,0,3,2] row_mask:0xf bank_mask:0xf
	s_waitcnt lgkmcnt(0)
	s_nop 1
	v_add_f32_dpp v9, v9, v9 quad_perm:[2,3,0,1] row_mask:0xf bank_mask:0xf
	ds_bpermute_b32 v11, v112, v9
	s_waitcnt lgkmcnt(0)
	v_add_f32_e32 v9, v9, v11
	ds_bpermute_b32 v11, v113, v9
	s_waitcnt lgkmcnt(0)
	v_add_f32_e32 v9, v9, v11
	ds_bpermute_b32 v11, v114, v9
	s_waitcnt lgkmcnt(0)
	v_add_f32_e32 v9, v9, v11
	ds_bpermute_b32 v11, v115, v9
	s_waitcnt lgkmcnt(0)
	v_add_f32_e32 v9, v9, v11
	v_fmamk_f32 v9, v9, 0x3a000000, v1
	v_mul_f32_e32 v11, 0x4b800000, v9
	v_cmp_gt_f32_e32 vcc, s18, v9
	s_nop 1
	v_cndmask_b32_e32 v9, v9, v11, vcc
	v_rsq_f32_e32 v9, v9
	s_nop 0
	v_mul_f32_e32 v11, 0x45800000, v9
	v_cndmask_b32_e32 v124, v9, v11, vcc
	v_pk_mul_f32 v[126:127], v[42:43], v[124:125] op_sel_hi:[1,0]
	v_pk_mul_f32 v[128:129], v[44:45], v[124:125] op_sel_hi:[1,0]
	s_waitcnt vmcnt(0)
	v_pk_fma_f32 v[116:117], v[116:117], v[126:127], v[120:121]
	v_pk_fma_f32 v[118:119], v[118:119], v[128:129], v[122:123]
	v_cvt_pk_bf16_f32 v126, v116, v117
	v_pk_mul_f32 v[130:131], v[38:39], v[124:125] op_sel_hi:[1,0]
	v_cvt_pk_bf16_f32 v127, v118, v119
	flat_load_dwordx4 v[116:119], v[80:81]
	flat_load_dwordx4 v[120:123], v[66:67]
	v_pk_mul_f32 v[132:133], v[40:41], v[124:125] op_sel_hi:[1,0]
	v_lshl_add_u64 v[128:129], v[96:97], 0, s[10:11]
	flat_store_dwordx2 v[128:129], v[126:127]
	s_waitcnt vmcnt(0) lgkmcnt(0)
	v_pk_fma_f32 v[118:119], v[118:119], v[132:133], v[122:123]
	v_pk_fma_f32 v[116:117], v[116:117], v[130:131], v[120:121]
	v_pk_mul_f32 v[130:131], v[34:35], v[124:125] op_sel_hi:[1,0]
	v_cvt_pk_bf16_f32 v126, v116, v117
	v_cvt_pk_bf16_f32 v127, v118, v119
	flat_load_dwordx4 v[116:119], v[82:83]
	flat_load_dwordx4 v[120:123], v[68:69]
	v_pk_mul_f32 v[132:133], v[36:37], v[124:125] op_sel_hi:[1,0]
	flat_store_dwordx2 v[128:129], v[126:127] offset:512
	s_waitcnt vmcnt(0) lgkmcnt(0)
	v_pk_fma_f32 v[118:119], v[118:119], v[132:133], v[122:123]
	v_pk_fma_f32 v[116:117], v[116:117], v[130:131], v[120:121]
	v_pk_mul_f32 v[130:131], v[30:31], v[124:125] op_sel_hi:[1,0]
	v_cvt_pk_bf16_f32 v126, v116, v117
	v_cvt_pk_bf16_f32 v127, v118, v119
	flat_load_dwordx4 v[116:119], v[84:85]
	flat_load_dwordx4 v[120:123], v[70:71]
	v_pk_mul_f32 v[132:133], v[32:33], v[124:125] op_sel_hi:[1,0]
	flat_store_dwordx2 v[128:129], v[126:127] offset:1024
	s_waitcnt vmcnt(0) lgkmcnt(0)
	v_pk_fma_f32 v[118:119], v[118:119], v[132:133], v[122:123]
	v_pk_fma_f32 v[116:117], v[116:117], v[130:131], v[120:121]
	v_pk_mul_f32 v[130:131], v[58:59], v[124:125] op_sel_hi:[1,0]
	v_cvt_pk_bf16_f32 v126, v116, v117
	v_cvt_pk_bf16_f32 v127, v118, v119
	flat_load_dwordx4 v[116:119], v[86:87]
	flat_load_dwordx4 v[120:123], v[72:73]
	v_pk_mul_f32 v[132:133], v[60:61], v[124:125] op_sel_hi:[1,0]
	flat_store_dwordx2 v[128:129], v[126:127] offset:1536
	s_waitcnt vmcnt(0) lgkmcnt(0)
	v_pk_fma_f32 v[118:119], v[118:119], v[132:133], v[122:123]
	v_pk_fma_f32 v[116:117], v[116:117], v[130:131], v[120:121]
	v_pk_mul_f32 v[130:131], v[54:55], v[124:125] op_sel_hi:[1,0]
	v_cvt_pk_bf16_f32 v126, v116, v117
	v_cvt_pk_bf16_f32 v127, v118, v119
	flat_load_dwordx4 v[116:119], v[88:89]
	flat_load_dwordx4 v[120:123], v[74:75]
	v_pk_mul_f32 v[132:133], v[56:57], v[124:125] op_sel_hi:[1,0]
	flat_store_dwordx2 v[128:129], v[126:127] offset:2048
	s_waitcnt vmcnt(0) lgkmcnt(0)
	v_pk_fma_f32 v[118:119], v[118:119], v[132:133], v[122:123]
	v_pk_fma_f32 v[116:117], v[116:117], v[130:131], v[120:121]
	v_pk_mul_f32 v[130:131], v[50:51], v[124:125] op_sel_hi:[1,0]
	v_cvt_pk_bf16_f32 v126, v116, v117
	v_cvt_pk_bf16_f32 v127, v118, v119
	flat_load_dwordx4 v[116:119], v[90:91]
	flat_load_dwordx4 v[120:123], v[76:77]
	v_pk_mul_f32 v[132:133], v[52:53], v[124:125] op_sel_hi:[1,0]
	flat_store_dwordx2 v[128:129], v[126:127] offset:2560
	s_waitcnt vmcnt(0) lgkmcnt(0)
	v_pk_fma_f32 v[118:119], v[132:133], v[118:119], v[122:123]
	v_pk_fma_f32 v[116:117], v[130:131], v[116:117], v[120:121]
	v_pk_mul_f32 v[130:131], v[46:47], v[124:125] op_sel_hi:[1,0]
	v_cvt_pk_bf16_f32 v126, v116, v117
	v_cvt_pk_bf16_f32 v127, v118, v119
	flat_load_dwordx4 v[116:119], v[92:93]
	flat_load_dwordx4 v[120:123], v[94:95]
	v_pk_mul_f32 v[124:125], v[48:49], v[124:125] op_sel_hi:[1,0]
	flat_store_dwordx2 v[128:129], v[126:127] offset:3072
	s_waitcnt vmcnt(0) lgkmcnt(0)
	v_pk_fma_f32 v[116:117], v[130:131], v[116:117], v[120:121]
	v_pk_fma_f32 v[118:119], v[124:125], v[118:119], v[122:123]
	v_cvt_pk_bf16_f32 v116, v116, v117
	s_nop 0
	v_cvt_pk_bf16_f32 v117, v118, v119
	flat_store_dwordx2 v[128:129], v[116:117] offset:3584

; __device__ __forceinline__ float wave_sum(float v) {
; #pragma unroll
;     for (int o = 1; o < 64; o <<= 1) v += __shfl_xor(v, o);
;     return v;
; __device__ __forceinline__ void ln_apply(f32x4 (&v)[8], const float* __restrict__ g, const float* __restrict__ b, bf16_t* hb, float* fo, int lane) {
;     float s = 0.f;
; #pragma unroll
;     for (int j = 0; j < 8; ++j) s += (v[j][0] + v[j][1]) + (v[j][2] + v[j][3]);
;     const float mean = wave_sum(s) * (1.f / DM); float q = 0.f;
; #pragma unroll
;     for (int j = 0; j < 8; ++j) { v[j] = v[j] - mean; q += (v[j][0] * v[j][0] + v[j][1] * v[j][1]) + (v[j][2] * v[j][2] + v[j][3] * v[j][3]); }
;     const float rstd = rsqrtf(wave_sum(q) * (1.f / DM) + LN_EPS);
.LBB0_2629:
	v_pk_add_f32 v[116:117], v[98:99], v[2:3]
	v_pk_add_f32 v[118:119], v[100:101], v[4:5]
	v_add_f32_e32 v11, v26, v27
	v_pk_add_f32 v[116:117], v[116:117], v[118:119]
	v_add_f32_e32 v23, v18, v19
	v_add_f32_e32 v9, 0, v117
	v_add_f32_e32 v105, v116, v9
	v_pk_add_f32 v[116:117], v[102:103], v[6:7]
	v_add_f32_e32 v9, v28, v29
	v_pk_add_f32 v[116:117], v[116:117], v[116:117] op_sel_hi:[0,1]
	v_mov_b32_e32 v13, v117
	v_pk_add_f32 v[118:119], v[10:11], v[8:9]
	v_pk_add_f32 v[116:117], v[12:13], v[104:105]
	v_add_f32_e32 v17, v20, v21
	v_pk_add_f32 v[116:117], v[118:119], v[116:117]
	v_pk_add_f32 v[118:119], v[106:107], v[14:15]
	v_pk_add_f32 v[116:117], v[116:117], v[116:117] op_sel_hi:[0,1]
	v_pk_add_f32 v[118:119], v[118:119], v[118:119] op_sel_hi:[0,1]
	v_mov_b32_e32 v25, v119
	v_mov_b32_e32 v109, v117
	v_pk_add_f32 v[120:121], v[22:23], v[16:17]
	v_pk_add_f32 v[116:117], v[24:25], v[108:109]
	s_ashr_i32 s9, s8, 31
	v_pk_add_f32 v[116:117], v[120:121], v[116:117]
	s_lshl_b64 s[12:13], s[8:9], 12
	v_add_f32_e32 v9, v116, v117
	s_cmpk_gt_i32 s10, 0x400f
	s_waitcnt lgkmcnt(0)
	s_nop 1
	v_add_f32_dpp v9, v9, v9 quad_perm:[1,0,3,2] row_mask:0xf bank_mask:0xf
	s_waitcnt lgkmcnt(0)
	s_nop 1
	v_add_f32_dpp v9, v9, v9 quad_perm:[2,3,0,1] row_mask:0xf bank_mask:0xf
	ds_bpermute_b32 v11, v112, v9
	s_waitcnt lgkmcnt(0)
	v_add_f32_e32 v9, v9, v11
	ds_bpermute_b32 v11, v113, v9
	s_waitcnt lgkmcnt(0)
	v_add_f32_e32 v9, v9, v11
	ds_bpermute_b32 v11, v114, v9
	s_waitcnt lgkmcnt(0)
	v_add_f32_e32 v9, v9, v11
	ds_bpermute_b32 v11, v115, v9
	s_waitcnt lgkmcnt(0)
	v_add_f32_e32 v9, v9, v11
	v_fmac_f32_e32 v3, 0xba000000, v9
	v_fmac_f32_e32 v2, 0xba000000, v9
	v_fmac_f32_e32 v99, 0xba000000, v9
	v_fmac_f32_e32 v98, 0xba000000, v9
	v_mov_b32_e32 v118, v3
	v_mov_b32_e32 v119, v2
	v_fmac_f32_e32 v5, 0xba000000, v9
	v_fmac_f32_e32 v4, 0xba000000, v9
	v_mov_b32_e32 v116, v99
	v_mov_b32_e32 v117, v98
	v_pk_mul_f32 v[118:119], v[118:119], v[118:119]
	v_fmac_f32_e32 v101, 0xba000000, v9
	v_fmac_f32_e32 v100, 0xba000000, v9
	v_pk_fma_f32 v[116:117], v[116:117], v[116:117], v[118:119]
	v_mov_b32_e32 v118, v5
	v_mov_b32_e32 v119, v4
	v_mov_b32_e32 v120, v101
	v_mov_b32_e32 v121, v100
	v_pk_mul_f32 v[118:119], v[118:119], v[118:119]
	v_fmac_f32_e32 v7, 0xba000000, v9
	v_pk_fma_f32 v[118:119], v[120:121], v[120:121], v[118:119]
	v_fmac_f32_e32 v103, 0xba000000, v9
	v_fmac_f32_e32 v102, 0xba000000, v9
	v_fmac_f32_e32 v6, 0xba000000, v9
	v_pk_add_f32 v[116:117], v[116:117], v[118:119]
	v_mov_b32_e32 v124, v103
	v_mov_b32_e32 v125, v7
	v_mov_b32_e32 v126, v6
	v_mov_b32_e32 v127, v102
	v_pk_add_f32 v[116:117], v[116:117], v[116:117] op_sel_hi:[0,1]
	v_pk_mul_f32 v[118:119], v[124:125], v[124:125]
	v_pk_mul_f32 v[120:121], v[126:127], v[126:127]
	v_fmac_f32_e32 v26, 0xba000000, v9
	v_pk_mov_b32 v[122:123], v[120:121], v[118:119] op_sel:[1,0]
	v_mov_b32_e32 v121, v119
	v_fmac_f32_e32 v28, 0xba000000, v9
	v_fmac_f32_e32 v27, 0xba000000, v9
	v_mul_f32_e32 v116, v26, v26
	v_pk_add_f32 v[118:119], v[122:123], v[120:121]
	v_fmac_f32_e32 v29, 0xba000000, v9
	v_pk_fma_f32 v[120:121], v[26:27], v[26:27], v[116:117] op_sel_hi:[1,1,0]
	v_mul_f32_e32 v116, v28, v28
	v_pk_add_f32 v[118:119], v[118:119], v[118:119] op_sel_hi:[0,1]
	v_pk_fma_f32 v[122:123], v[28:29], v[28:29], v[116:117] op_sel_hi:[1,1,0]
	v_fmac_f32_e32 v104, 0xba000000, v9
	v_fmac_f32_e32 v12, 0xba000000, v9
	v_fmac_f32_e32 v8, 0xba000000, v9
	v_fmac_f32_e32 v10, 0xba000000, v9
	v_mul_f32_e32 v120, v10, v10
	v_mul_f32_e32 v122, v8, v8
	v_mul_f32_e32 v118, v12, v12
	v_mul_f32_e32 v116, v104, v104
	v_pk_add_f32 v[120:121], v[120:121], v[122:123]
	v_pk_add_f32 v[116:117], v[118:119], v[116:117]
	v_fmac_f32_e32 v15, 0xba000000, v9
	v_pk_add_f32 v[116:117], v[120:121], v[116:117]
	v_fmac_f32_e32 v107, 0xba000000, v9
	v_pk_add_f32 v[128:129], v[116:117], v[116:117] op_sel_hi:[0,1]
	flat_load_dwordx4 v[116:119], v[78:79]
	flat_load_dwordx4 v[120:123], v[64:65]
	v_fmac_f32_e32 v106, 0xba000000, v9
	v_fmac_f32_e32 v14, 0xba000000, v9
	v_mov_b32_e32 v130, v107
	v_mov_b32_e32 v131, v15
	v_mov_b32_e32 v134, v14
	v_mov_b32_e32 v135, v106
	v_pk_mul_f32 v[132:133], v[130:131], v[130:131]
	v_pk_mul_f32 v[136:137], v[134:135], v[134:135]
	v_fmac_f32_e32 v18, 0xba000000, v9
	v_pk_mov_b32 v[138:139], v[136:137], v[132:133] op_sel:[1,0]
	v_mov_b32_e32 v137, v133
	v_fmac_f32_e32 v20, 0xba000000, v9
	v_fmac_f32_e32 v19, 0xba000000, v9
	v_mul_f32_e32 v128, v18, v18
	v_pk_add_f32 v[132:133], v[138:139], v[136:137]
	v_fmac_f32_e32 v21, 0xba000000, v9
	v_pk_fma_f32 v[136:137], v[18:19], v[18:19], v[128:129] op_sel_hi:[1,1,0]
	v_mul_f32_e32 v128, v20, v20
	v_pk_add_f32 v[132:133], v[132:133], v[132:133] op_sel_hi:[0,1]
	v_pk_fma_f32 v[138:139], v[20:21], v[20:21], v[128:129] op_sel_hi:[1,1,0]
	v_fmac_f32_e32 v108, 0xba000000, v9
	v_fmac_f32_e32 v24, 0xba000000, v9
	v_fmac_f32_e32 v16, 0xba000000, v9
	v_fmac_f32_e32 v22, 0xba000000, v9
	v_mul_f32_e32 v136, v22, v22
	v_mul_f32_e32 v138, v16, v16
	v_mul_f32_e32 v132, v24, v24
	v_mul_f32_e32 v128, v108, v108
	v_pk_add_f32 v[136:137], v[136:137], v[138:139]
	v_pk_add_f32 v[128:129], v[132:133], v[128:129]
	v_mov_b32_e32 v132, v101
	v_pk_add_f32 v[128:129], v[136:137], v[128:129]
	v_mov_b32_e32 v133, v5
	v_add_f32_e32 v9, v128, v129
	v_mov_b32_e32 v128, v99
	v_mov_b32_e32 v129, v3
	v_mov_b32_e32 v138, v98
	v_mov_b32_e32 v139, v2
	s_waitcnt lgkmcnt(0)
	s_nop 1
	v_add_f32_dpp v9, v9, v9 quad_perm:[1,0,3,2] row_mask:0xf bank_mask:0xf
	v_mov_b32_e32 v140, v100
	v_mov_b32_e32 v141, v4
	v_mov_b32_e32 v13, v104
	v_mov_b32_e32 v23, v16
	s_waitcnt lgkmcnt(0)
; __device__ __forceinline__ unsigned cvt_pk_bf16(float lo, float hi) { unsigned r; asm volatile("v_cvt_pk_bf16_f32 %0, %1, %2" : "=v"(r) : "v"(lo), "v"(hi)); return r; }
; __device__ __forceinline__ void ln_apply(f32x4 (&v)[8], const float* __restrict__ g, const float* __restrict__ b, bf16_t* hb, float* fo, int lane) {
;     ...
;     const float rstd = rsqrtf(wave_sum(q) * (1.f / DM) + LN_EPS);
; #pragma unroll
;     for (int j = 0; j < 8; ++j) { const int c = (lane + 64 * j) * 4; const f32x4 gg = *(const f32x4*)(g + c), bb = *(const f32x4*)(b + c);
;         const f32x4 y = v[j] * rstd * gg + bb;
;         if (hb) { u32x2 w; w.x = cvt_pk_bf16(y[0], y[1]); w.y = cvt_pk_bf16(y[2], y[3]); *(u32x2*)(hb + c) = w; }
	s_nop 1
	v_add_f32_dpp v9, v9, v9 quad_perm:[2,3,0,1] row_mask:0xf bank_mask:0xf
	ds_bpermute_b32 v11, v112, v9
	v_mov_b32_e32 v25, v108
	s_waitcnt lgkmcnt(0)
	v_add_f32_e32 v9, v9, v11
	ds_bpermute_b32 v11, v113, v9
	s_waitcnt lgkmcnt(0)
	v_add_f32_e32 v9, v9, v11
	ds_bpermute_b32 v11, v114, v9
	s_waitcnt lgkmcnt(0)
	v_add_f32_e32 v9, v9, v11
	ds_bpermute_b32 v11, v115, v9
	s_waitcnt lgkmcnt(0)
	v_add_f32_e32 v9, v9, v11
	v_fmamk_f32 v9, v9, 0x3a000000, v1
	v_mul_f32_e32 v11, 0x4b800000, v9
	v_cmp_gt_f32_e32 vcc, s18, v9
	s_nop 1
	v_cndmask_b32_e32 v9, v9, v11, vcc
	v_rsq_f32_e32 v9, v9
	s_nop 0
	v_mul_f32_e32 v11, 0x45800000, v9
	v_cndmask_b32_e32 v136, v9, v11, vcc
	v_pk_mul_f32 v[128:129], v[128:129], v[136:137] op_sel_hi:[1,0]
	v_pk_mul_f32 v[132:133], v[132:133], v[136:137] op_sel_hi:[1,0]
	s_waitcnt vmcnt(0)
	v_pk_fma_f32 v[116:117], v[116:117], v[128:129], v[120:121]
	v_pk_fma_f32 v[118:119], v[118:119], v[132:133], v[122:123]
	v_cvt_pk_bf16_f32 v128, v116, v117
	v_pk_mul_f32 v[138:139], v[138:139], v[136:137] op_sel_hi:[1,0]
	v_cvt_pk_bf16_f32 v129, v118, v119
	flat_load_dwordx4 v[116:119], v[80:81]
	flat_load_dwordx4 v[120:123], v[66:67]
	v_pk_mul_f32 v[140:141], v[140:141], v[136:137] op_sel_hi:[1,0]
	v_lshl_add_u64 v[132:133], v[96:97], 0, s[12:13]
	flat_store_dwordx2 v[132:133], v[128:129]
	v_pk_mul_f32 v[126:127], v[126:127], v[136:137] op_sel_hi:[1,0]
	v_pk_mul_f32 v[124:125], v[124:125], v[136:137] op_sel_hi:[1,0]
	v_mov_b32_e32 v11, v8
	s_mov_b64 s[12:13], -1
	s_waitcnt vmcnt(0) lgkmcnt(0)
	v_pk_fma_f32 v[118:119], v[118:119], v[140:141], v[122:123]
	v_pk_fma_f32 v[116:117], v[116:117], v[138:139], v[120:121]
	s_nop 0
	v_cvt_pk_bf16_f32 v128, v116, v117
	v_cvt_pk_bf16_f32 v129, v118, v119
	flat_load_dwordx4 v[116:119], v[82:83]
	flat_load_dwordx4 v[120:123], v[68:69]
	s_waitcnt vmcnt(0) lgkmcnt(0)
	v_pk_fma_f32 v[118:119], v[118:119], v[124:125], v[122:123]
	v_pk_fma_f32 v[116:117], v[116:117], v[126:127], v[120:121]
	flat_store_dwordx2 v[132:133], v[128:129] offset:512
	v_cvt_pk_bf16_f32 v124, v116, v117
	v_cvt_pk_bf16_f32 v125, v118, v119
	flat_load_dwordx4 v[116:119], v[84:85]
	flat_load_dwordx4 v[120:123], v[70:71]
	v_pk_mul_f32 v[126:127], v[26:27], v[136:137] op_sel_hi:[1,0]
	v_pk_mul_f32 v[128:129], v[28:29], v[136:137] op_sel_hi:[1,0]
	flat_store_dwordx2 v[132:133], v[124:125] offset:1024
	s_waitcnt vmcnt(0) lgkmcnt(0)
	v_pk_fma_f32 v[118:119], v[118:119], v[128:129], v[122:123]
	v_pk_fma_f32 v[116:117], v[116:117], v[126:127], v[120:121]
	v_pk_mul_f32 v[126:127], v[10:11], v[136:137] op_sel_hi:[1,0]
	v_cvt_pk_bf16_f32 v124, v116, v117
	v_cvt_pk_bf16_f32 v125, v118, v119
	flat_load_dwordx4 v[116:119], v[86:87]
	flat_load_dwordx4 v[120:123], v[72:73]
	v_pk_mul_f32 v[128:129], v[12:13], v[136:137] op_sel_hi:[1,0]
	flat_store_dwordx2 v[132:133], v[124:125] offset:1536
	s_waitcnt vmcnt(0) lgkmcnt(0)
	v_pk_fma_f32 v[118:119], v[118:119], v[128:129], v[122:123]
	v_pk_fma_f32 v[116:117], v[116:117], v[126:127], v[120:121]
	v_pk_mul_f32 v[126:127], v[134:135], v[136:137] op_sel_hi:[1,0]
	v_cvt_pk_bf16_f32 v124, v116, v117
	v_cvt_pk_bf16_f32 v125, v118, v119
	flat_load_dwordx4 v[116:119], v[88:89]
	flat_load_dwordx4 v[120:123], v[74:75]
	v_pk_mul_f32 v[128:129], v[130:131], v[136:137] op_sel_hi:[1,0]
	flat_store_dwordx2 v[132:133], v[124:125] offset:2048
	s_waitcnt vmcnt(0) lgkmcnt(0)
	v_pk_fma_f32 v[118:119], v[118:119], v[128:129], v[122:123]
	v_pk_fma_f32 v[116:117], v[116:117], v[126:127], v[120:121]
	v_pk_mul_f32 v[126:127], v[18:19], v[136:137] op_sel_hi:[1,0]
	v_cvt_pk_bf16_f32 v124, v116, v117
	v_cvt_pk_bf16_f32 v125, v118, v119
	flat_load_dwordx4 v[116:119], v[90:91]
	flat_load_dwordx4 v[120:123], v[76:77]
	v_pk_mul_f32 v[128:129], v[20:21], v[136:137] op_sel_hi:[1,0]
	flat_store_dwordx2 v[132:133], v[124:125] offset:2560
	s_waitcnt vmcnt(0) lgkmcnt(0)
	v_pk_fma_f32 v[118:119], v[128:129], v[118:119], v[122:123]
	v_pk_fma_f32 v[116:117], v[126:127], v[116:117], v[120:121]
	v_pk_mul_f32 v[126:127], v[22:23], v[136:137] op_sel_hi:[1,0]
	v_cvt_pk_bf16_f32 v124, v116, v117
	v_cvt_pk_bf16_f32 v125, v118, v119
	flat_load_dwordx4 v[116:119], v[92:93]
	flat_load_dwordx4 v[120:123], v[94:95]
	v_pk_mul_f32 v[128:129], v[24:25], v[136:137] op_sel_hi:[1,0]
	flat_store_dwordx2 v[132:133], v[124:125] offset:3072
	s_waitcnt vmcnt(0) lgkmcnt(0)
	v_pk_fma_f32 v[116:117], v[126:127], v[116:117], v[120:121]
	v_pk_fma_f32 v[118:119], v[128:129], v[118:119], v[122:123]
	v_cvt_pk_bf16_f32 v116, v116, v117
	s_nop 0
	v_cvt_pk_bf16_f32 v117, v118, v119
	flat_store_dwordx2 v[132:133], v[116:117] offset:3584
	s_cbranch_scc1 .LBB0_2626
	s_add_i32 s14, s10, s3
	s_cmpk_gt_i32 s14, 0x400f
	s_cselect_b64 s[12:13], -1, 0
	s_and_b64 vcc, exec, s[12:13]
	s_cbranch_vccnz .LBB0_2625
	s_ashr_i32 s15, s14, 31
	s_lshl_b64 s[8:9], s[14:15], 13
	v_lshl_add_u64 v[98:99], v[62:63], 0, s[8:9]
	flat_load_dwordx4 v[2:5], v[98:99]
	flat_load_dwordx4 v[102:105], v[98:99] offset:1024
	flat_load_dwordx4 v[6:9], v[98:99] offset:2048
	v_add_co_u32_e32 v100, vcc, 0x1000, v98
	s_mov_b32 s8, s14
	s_nop 0
	v_addc_co_u32_e32 v101, vcc, 0, v99, vcc
	flat_load_dwordx4 v[10:13], v[100:101]
	flat_load_dwordx4 v[14:17], v[100:101] offset:1024
	flat_load_dwordx4 v[22:25], v[100:101] offset:3072
	flat_load_dwordx4 v[18:21], v[100:101] offset:2048
	flat_load_dwordx4 v[26:29], v[98:99] offset:3072
	s_waitcnt vmcnt(0) lgkmcnt(0)
	v_mov_b32_e32 v99, v2
	v_mov_b32_e32 v101, v4
	v_mov_b32_e32 v98, v102
	v_mov_b32_e32 v2, v103
	v_mov_b32_e32 v100, v104
	v_mov_b32_e32 v4, v105
	v_mov_b32_e32 v102, v7
	v_mov_b32_e32 v103, v8
	v_mov_b32_e32 v7, v9
	v_mov_b32_e32 v8, v11
	v_mov_b32_e32 v104, v13
	v_mov_b32_e32 v106, v15
	v_mov_b32_e32 v107, v16
	v_mov_b32_e32 v15, v17
	v_mov_b32_e32 v16, v23
	v_mov_b32_e32 v108, v25
	s_branch .LBB0_2625
